# v23 plus weight conversion up-proj copy: scale and row loads all in flight, counted waits
# baseline (speedup 1.0000x reference)
; DI int tid_() { int t = threadIdx.x; asm volatile("" : "+v"(t)); return t; }
; DI void conv_tile(const ConvJob& J, int t, lptr lds) {
;     const int tid = tid_(); const int nkt = J.K / 64;
;     const int kt = t % nkt, nt = t / nkt; const int k0 = kt * 64, n0d = nt * 256, n0s = n0d + (n0d >= J.split ? 8 : 0);
; #pragma unroll
;     for (int it = 0; it < 8; ++it) { const int kr = it * 8 + (tid >> 6), nc = (tid & 63) * 4;
;         int scol = n0s + nc;
;         if (n0d >= J.rlo && n0d < J.rhi) { const int d = n0d + nc - J.rlo, jj = d & 63, chunk = jj >> 3; scol = J.rlo + (n0s - n0d) + (d & ~63) + ((jj & 4) ? 32 + 4 * chunk : 4 * chunk); }
;         const f32x4 v = *(const f32x4*)(J.W + (size_t)(k0 + kr) * J.ldn + scol);
;         const float rsc = J.rs ? J.rs[k0 + kr] : 1.f;
.LBB0_115:
	s_andn2_b64 vcc, exec, s[2:3]
	s_cbranch_vccnz .LBB0_133
	s_add_i32 s2, s50, s56
	s_sub_i32 s2, s2, 64
	s_ashr_i32 s3, s2, 31
	s_lshr_b32 s3, s3, 28
	s_add_i32 s3, s2, s3
	s_and_b32 s38, s3, 0x3fffff0
	v_mov_b32_e32 v19, v194
	s_sub_i32 s2, s2, s38
	s_lshl_b32 s2, s2, 6
	v_ashrrev_i32_e32 v17, 6, v19
	s_lshl_b32 s3, s3, 4
	v_lshlrev_b32_e32 v0, 2, v19
	v_add_u32_e32 v12, s2, v17
	s_and_b32 s3, s3, 0xffffff00
	v_and_b32_e32 v16, 0xfc, v0
	v_ashrrev_i32_e32 v13, 31, v12
	v_or_b32_e32 v10, s3, v16
	v_lshlrev_b64 v[2:3], 14, v[12:13]
	v_lshl_add_u64 v[2:3], s[44:45], 0, v[2:3]
	v_ashrrev_i32_e32 v11, 31, v10
	v_lshl_add_u64 v[2:3], v[10:11], 2, v[2:3]
	v_readlane_b32 s36, v250, 56
	v_readlane_b32 s37, v250, 57
	v_lshl_add_u64 v[14:15], v[12:13], 2, s[46:47]
	v_mov_b32_e32 v128, 1.0
	v_mov_b32_e32 v130, 1.0
	v_mov_b32_e32 v132, 1.0
	v_mov_b32_e32 v136, 1.0
	v_mov_b32_e32 v138, 1.0
	v_mov_b32_e32 v140, 1.0
	v_mov_b32_e32 v142, 1.0
	v_mov_b32_e32 v144, 1.0
	s_andn2_b64 vcc, exec, s[36:37]
	s_cbranch_vccnz .Lmy_up_nors
	global_load_dword v128, v[14:15], off
	global_load_dword v130, v[14:15], off offset:32
	global_load_dword v132, v[14:15], off offset:64
	global_load_dword v136, v[14:15], off offset:96
	global_load_dword v138, v[14:15], off offset:128
	global_load_dword v140, v[14:15], off offset:160
	global_load_dword v142, v[14:15], off offset:192
	global_load_dword v144, v[14:15], off offset:224
; DI unsigned pk2(float lo, float hi) { f32x2_t v = {lo, hi}; bf16x2_t b = __builtin_convertvector(v, bf16x2_t); return __builtin_bit_cast(unsigned, b); }
; DI int tid_() { int t = threadIdx.x; asm volatile("" : "+v"(t)); return t; }
; DI void conv_tile(const ConvJob& J, int t, lptr lds) {
;     const int tid = tid_(); const int nkt = J.K / 64;
;     const int kt = t % nkt, nt = t / nkt; const int k0 = kt * 64, n0d = nt * 256, n0s = n0d + (n0d >= J.split ? 8 : 0);
; #pragma unroll
;     for (int it = 0; it < 8; ++it) { const int kr = it * 8 + (tid >> 6), nc = (tid & 63) * 4;
;         int scol = n0s + nc;
;         if (n0d >= J.rlo && n0d < J.rhi) { const int d = n0d + nc - J.rlo, jj = d & 63, chunk = jj >> 3; scol = J.rlo + (n0s - n0d) + (d & ~63) + ((jj & 4) ? 32 + 4 * chunk : 4 * chunk); }
;         const f32x4 v = *(const f32x4*)(J.W + (size_t)(k0 + kr) * J.ldn + scol);
;         const float rsc = J.rs ? J.rs[k0 + kr] : 1.f;
;         lst<f32x4>(lds, (kr * 260 + nc) * 4, v * rsc); }
;     __syncthreads();
;     { const int n = tid >> 1, kh = (tid & 1) * 32;
; #pragma unroll
;         for (int q = 0; q < 4; ++q) { float v[8];
;             for (int e = 0; e < 8; ++e) v[e] = lld<float>(lds, ((kh + 8 * q + e) * 260 + n) * 4);
;             u32x4 w; w.x = pk2(v[0], v[1]); w.y = pk2(v[2], v[3]); w.z = pk2(v[4], v[5]); w.w = pk2(v[6], v[7]);
;             *(u32x4*)(J.Wt + (size_t)(n0d + n) * J.K + k0 + kh + 8 * q) = w; } }
;     __syncthreads();
.Lmy_up_nors:
	global_load_dwordx4 v[96:99], v[2:3], off
	v_add_u32_e32 v6, 8, v12
	v_ashrrev_i32_e32 v7, 31, v6
	v_lshlrev_b64 v[6:7], 14, v[6:7]
	v_lshl_add_u64 v[6:7], s[44:45], 0, v[6:7]
	v_lshl_add_u64 v[6:7], v[10:11], 2, v[6:7]
	global_load_dwordx4 v[100:103], v[6:7], off
	v_add_u32_e32 v6, 16, v12
	v_ashrrev_i32_e32 v7, 31, v6
	v_lshlrev_b64 v[6:7], 14, v[6:7]
	v_lshl_add_u64 v[6:7], s[44:45], 0, v[6:7]
	v_lshl_add_u64 v[6:7], v[10:11], 2, v[6:7]
	global_load_dwordx4 v[104:107], v[6:7], off
	v_add_u32_e32 v6, 24, v12
	v_ashrrev_i32_e32 v7, 31, v6
	v_lshlrev_b64 v[6:7], 14, v[6:7]
	v_lshl_add_u64 v[6:7], s[44:45], 0, v[6:7]
	v_lshl_add_u64 v[6:7], v[10:11], 2, v[6:7]
	global_load_dwordx4 v[108:111], v[6:7], off
	v_add_u32_e32 v6, 32, v12
	v_ashrrev_i32_e32 v7, 31, v6
	v_lshlrev_b64 v[6:7], 14, v[6:7]
	v_lshl_add_u64 v[6:7], s[44:45], 0, v[6:7]
	v_lshl_add_u64 v[6:7], v[10:11], 2, v[6:7]
	global_load_dwordx4 v[112:115], v[6:7], off
	v_add_u32_e32 v6, 40, v12
	v_ashrrev_i32_e32 v7, 31, v6
	v_lshlrev_b64 v[6:7], 14, v[6:7]
	v_lshl_add_u64 v[6:7], s[44:45], 0, v[6:7]
	v_lshl_add_u64 v[6:7], v[10:11], 2, v[6:7]
	global_load_dwordx4 v[116:119], v[6:7], off
	v_add_u32_e32 v6, 48, v12
	v_ashrrev_i32_e32 v7, 31, v6
	v_lshlrev_b64 v[6:7], 14, v[6:7]
	v_lshl_add_u64 v[6:7], s[44:45], 0, v[6:7]
	v_lshl_add_u64 v[6:7], v[10:11], 2, v[6:7]
	global_load_dwordx4 v[120:123], v[6:7], off
	v_add_u32_e32 v6, 56, v12
	v_ashrrev_i32_e32 v7, 31, v6
	v_lshlrev_b64 v[6:7], 14, v[6:7]
	v_lshl_add_u64 v[6:7], s[44:45], 0, v[6:7]
	v_lshl_add_u64 v[6:7], v[10:11], 2, v[6:7]
	global_load_dwordx4 v[124:127], v[6:7], off
	s_movk_i32 s36, 0x104
	v_mad_u64_u32 v[16:17], s[58:59], v17, s36, v[16:17]
	v_lshl_add_u32 v13, v16, 2, 0
	s_waitcnt vmcnt(7)
	v_pk_mul_f32 v[96:97], v[96:97], v[128:129] op_sel_hi:[1,0]
	v_pk_mul_f32 v[98:99], v[98:99], v[128:129] op_sel_hi:[1,0]
	ds_write_b128 v13, v[96:99]
	s_waitcnt vmcnt(6)
	v_pk_mul_f32 v[100:101], v[100:101], v[130:131] op_sel_hi:[1,0]
	v_pk_mul_f32 v[102:103], v[102:103], v[130:131] op_sel_hi:[1,0]
	ds_write_b128 v13, v[100:103] offset:8320
	s_waitcnt vmcnt(5)
	v_pk_mul_f32 v[104:105], v[104:105], v[132:133] op_sel_hi:[1,0]
	v_pk_mul_f32 v[106:107], v[106:107], v[132:133] op_sel_hi:[1,0]
	ds_write_b128 v13, v[104:107] offset:16640
	s_waitcnt vmcnt(4)
	v_pk_mul_f32 v[108:109], v[108:109], v[136:137] op_sel_hi:[1,0]
	v_pk_mul_f32 v[110:111], v[110:111], v[136:137] op_sel_hi:[1,0]
	ds_write_b128 v13, v[108:111] offset:24960
	s_waitcnt vmcnt(3)
	v_pk_mul_f32 v[112:113], v[112:113], v[138:139] op_sel_hi:[1,0]
	v_pk_mul_f32 v[114:115], v[114:115], v[138:139] op_sel_hi:[1,0]
	ds_write_b128 v13, v[112:115] offset:33280
	s_waitcnt vmcnt(2)
	v_pk_mul_f32 v[116:117], v[116:117], v[140:141] op_sel_hi:[1,0]
	v_pk_mul_f32 v[118:119], v[118:119], v[140:141] op_sel_hi:[1,0]
	ds_write_b128 v13, v[116:119] offset:41600
	s_waitcnt vmcnt(1)
	v_pk_mul_f32 v[120:121], v[120:121], v[142:143] op_sel_hi:[1,0]
	v_pk_mul_f32 v[122:123], v[122:123], v[142:143] op_sel_hi:[1,0]
	ds_write_b128 v13, v[120:123] offset:49920
	s_waitcnt vmcnt(0)
	v_pk_mul_f32 v[124:125], v[124:125], v[144:145] op_sel_hi:[1,0]
	v_pk_mul_f32 v[126:127], v[126:127], v[144:145] op_sel_hi:[1,0]
	ds_write_b128 v13, v[124:127] offset:58240
	v_ashrrev_i32_e32 v0, 1, v19
	v_lshlrev_b32_e32 v2, 5, v19
	v_and_b32_e32 v8, 32, v2
	v_add_u32_e32 v6, s3, v0
	s_movk_i32 s3, 0x104
	v_mad_u32_u24 v0, v8, s3, v0
	v_lshl_add_u32 v9, v0, 2, 0
	s_waitcnt lgkmcnt(0)
	s_barrier
	ds_read_b32 v0, v9
	ds_read_b32 v2, v9 offset:1040
	ds_read_b32 v3, v9 offset:2080
	ds_read_b32 v4, v9 offset:3120
	ds_read_b32 v5, v9 offset:4160
	ds_read_b32 v10, v9 offset:5200
	ds_read_b32 v11, v9 offset:6240
	ds_read_b32 v12, v9 offset:7280
	v_ashrrev_i32_e32 v7, 31, v6
	v_readlane_b32 s36, v250, 47
	v_lshlrev_b64 v[6:7], 11, v[6:7]
	v_readlane_b32 s37, v250, 48
	s_ashr_i32 s3, s2, 31
	s_waitcnt lgkmcnt(6)
	v_cvt_pk_bf16_f32 v2, v0, v2
	v_lshl_add_u64 v[6:7], s[36:37], 0, v[6:7]
	v_lshl_add_u64 v[6:7], s[2:3], 1, v[6:7]
	v_lshlrev_b32_e32 v0, 1, v8
	s_waitcnt lgkmcnt(4)
	v_cvt_pk_bf16_f32 v3, v3, v4
	s_waitcnt lgkmcnt(2)
	v_cvt_pk_bf16_f32 v4, v5, v10
	s_waitcnt lgkmcnt(0)
	v_cvt_pk_bf16_f32 v5, v11, v12
	v_lshl_add_u64 v[6:7], v[6:7], 0, v[0:1]
	ds_read_b32 v0, v9 offset:8320
	ds_read_b32 v8, v9 offset:9360
	ds_read_b32 v10, v9 offset:10400
	ds_read_b32 v11, v9 offset:11440
	ds_read_b32 v12, v9 offset:12480
	ds_read_b32 v13, v9 offset:13520
	ds_read_b32 v14, v9 offset:14560
	ds_read_b32 v15, v9 offset:15600
	global_store_dwordx4 v[6:7], v[2:5], off
	s_waitcnt lgkmcnt(6)
	s_nop 0
	v_cvt_pk_bf16_f32 v2, v0, v8
	s_waitcnt lgkmcnt(4)
	v_cvt_pk_bf16_f32 v3, v10, v11
	s_waitcnt lgkmcnt(2)
	v_cvt_pk_bf16_f32 v4, v12, v13
	s_waitcnt lgkmcnt(0)
	v_cvt_pk_bf16_f32 v5, v14, v15
	ds_read_b32 v0, v9 offset:16640
	ds_read_b32 v8, v9 offset:17680
	ds_read_b32 v10, v9 offset:18720
	ds_read_b32 v11, v9 offset:19760
	ds_read_b32 v12, v9 offset:20800
	ds_read_b32 v13, v9 offset:21840
	ds_read_b32 v14, v9 offset:22880
	ds_read_b32 v15, v9 offset:23920
	global_store_dwordx4 v[6:7], v[2:5], off offset:16
	s_waitcnt lgkmcnt(6)
	s_nop 0
	v_cvt_pk_bf16_f32 v2, v0, v8
	s_waitcnt lgkmcnt(4)
	v_cvt_pk_bf16_f32 v3, v10, v11
	s_waitcnt lgkmcnt(2)
	v_cvt_pk_bf16_f32 v4, v12, v13
	s_waitcnt lgkmcnt(0)
	v_cvt_pk_bf16_f32 v5, v14, v15
	ds_read_b32 v0, v9 offset:24960
	ds_read_b32 v8, v9 offset:26000
	ds_read_b32 v10, v9 offset:27040
	ds_read_b32 v11, v9 offset:28080
	ds_read_b32 v12, v9 offset:29120
	ds_read_b32 v13, v9 offset:30160
	ds_read_b32 v14, v9 offset:31200
	ds_read_b32 v9, v9 offset:32240
	global_store_dwordx4 v[6:7], v[2:5], off offset:32
	s_waitcnt lgkmcnt(6)
	s_nop 0
	v_cvt_pk_bf16_f32 v2, v0, v8
	s_waitcnt lgkmcnt(4)
	v_cvt_pk_bf16_f32 v3, v10, v11
	s_waitcnt lgkmcnt(2)
	v_cvt_pk_bf16_f32 v4, v12, v13
	s_waitcnt lgkmcnt(0)
	v_cvt_pk_bf16_f32 v5, v14, v9
	global_store_dwordx4 v[6:7], v[2:5], off offset:48
	s_barrier
